# attention: K/V ds_reads interleaved into MFMA gaps (depth 4) + loop-invariant lane-index VALU hoisted out of tile loop, final row-sum via permlane32_swap
# speedup vs baseline: 1.0377x; 1.0071x over previous
; #define LAS __attribute__((address_space(3)))
; __device__ __forceinline__ void unit(LAS unsigned char* lds, const bf16* __restrict__ Q, const bf16* __restrict__ Kn, const bf16* __restrict__ Kr, const bf16* __restrict__ Vt, bf16* __restrict__ O,
;                                      int tokbase, int S, int h, int qb, const int tid) {
;     ...
;         {
;             bf16x8 vfa[2][2], vfb[2][2];
; #pragma unroll
;             for (int kt = 0; kt < 2; ++kt)
; #pragma unroll
;                 for (int s = 0; s < 2; ++s) {
;                     const int kcol = (kt * 32 + 16 * s + 4 * hi) * 2;
;                     const u32x2 a0 = *(const LAS u32x2*)(vb + r32 * VSTR + kcol), a1 = *(const LAS u32x2*)(vb + r32 * VSTR + kcol + 16);
;                     const u32x2 b0 = *(const LAS u32x2*)(vb + (32 + r32) * VSTR + kcol), b1 = *(const LAS u32x2*)(vb + (32 + r32) * VSTR + kcol + 16);
;                     vfa[kt][s] = __builtin_bit_cast(bf16x8, (u32x4){a0.x, a0.y, a1.x, a1.y});
;                     vfb[kt][s] = __builtin_bit_cast(bf16x8, (u32x4){b0.x, b0.y, b1.x, b1.y});
;                 }
;             __builtin_amdgcn_sched_barrier(0);
; #pragma unroll
;             for (int kt = 0; kt < 2; ++kt)
; #pragma unroll
;                 for (int s = 0; s < 2; ++s) {
;                     o0 = __builtin_amdgcn_mfma_f32_32x32x16_bf16(vfa[kt][s], pb[kt][s], o0, 0, 0, 0);
;                     o1 = __builtin_amdgcn_mfma_f32_32x32x16_bf16(vfb[kt][s], pb[kt][s], o1, 0, 0, 0);
;                 }
;         }
;         if (t + 1 < NT) ATT_WRITE((t + 1) & 1);
;         __syncthreads();
;     }
;     ...
;     l_run += __shfl_xor(l_run, 32);
;     const float inv = 1.0f / l_run;
;     LAS unsigned char* stg = lds + OST_OFF + wid * OST_WAVE;
; #pragma unroll
;     for (int r = 0; r < 16; ++r) { const int d = crow(r, hi);
;         *(LAS bf16*)(stg + r32 * 144 + d * 2) = f2bf(o0[r] * inv);
;         *(LAS bf16*)(stg + r32 * 144 + (32 + d) * 2) = f2bf(o1[r] * inv); }
;     asm volatile("s_waitcnt lgkmcnt(0)" ::: "memory");
;     bf16* Ow = O + (size_t)(tokbase + qb * 256 + wid * 32) * 1024 + h * 64;
; #pragma unroll
;     for (int i = 0; i < 4; ++i) { const int row = i * 8 + (lane >> 3), ch = lane & 7; const u32x4 v = *(const LAS u32x4*)(stg + row * 144 + ch * 16); *(u32x4*)(Ow + (size_t)row * 1024 + ch * 8) = v; }
.LBB0_718:
	v_add3_u32 v34, s37, v170, v169
	v_cvt_pk_bf16_f32 v46, v74, v75
	v_cvt_pk_bf16_f32 v48, v78, v79
	v_cvt_pk_bf16_f32 v38, v66, v67
	v_cvt_pk_bf16_f32 v39, v68, v69
	v_cvt_pk_bf16_f32 v40, v70, v71
	v_cvt_pk_bf16_f32 v41, v72, v73
	v_cvt_pk_bf16_f32 v47, v76, v77
	v_cvt_pk_bf16_f32 v49, v80, v81
	ds_read_b128 v[50:53], v34 offset:13312
	ds_read_b128 v[54:57], v34 offset:13344
	ds_read_b128 v[58:61], v34 offset:17920
	ds_read_b128 v[62:65], v34 offset:17952
	ds_read_b128 v[66:69], v34 offset:13376
	ds_read_b128 v[70:73], v34 offset:17984
	ds_read_b128 v[74:77], v34 offset:13408
	ds_read_b128 v[78:81], v34 offset:18016
	v_cvt_pk_bf16_f32 v34, v82, v83
	v_cvt_pk_bf16_f32 v35, v84, v85
	v_cvt_pk_bf16_f32 v36, v86, v87
	v_cvt_pk_bf16_f32 v37, v88, v89
	v_cvt_pk_bf16_f32 v42, v90, v91
	v_cvt_pk_bf16_f32 v43, v92, v93
	v_cvt_pk_bf16_f32 v44, v94, v95
	v_cvt_pk_bf16_f32 v45, v96, v97
	s_waitcnt lgkmcnt(7)
	v_mfma_f32_32x32x16_bf16 v[2:17], v[50:53], v[34:37], v[2:17]
	s_mulk_i32 s21, 0x1200
	s_waitcnt lgkmcnt(0)
	s_barrier
	v_mov_b32_e32 v157, v1
	v_mov_b32_e32 v159, v1
	v_mfma_f32_32x32x16_bf16 v[18:33], v[58:61], v[34:37], v[18:33]
	v_add_f32_e32 v34, v153, v98
	v_mov_b32_e32 v153, v1
	v_mov_b32_e32 v155, v1
	v_mov_b32_e32 v35, v34
	s_nop 1
	v_permlane32_swap_b32_e32 v35, v34
	v_add_f32_e32 v34, v34, v35
	v_mfma_f32_32x32x16_bf16 v[2:17], v[54:57], v[42:45], v[2:17]
	v_div_scale_f32 v35, s[26:27], v34, v34, 1.0
	v_rcp_f32_e32 v36, v35
	s_add_i32 s26, s21, 0
	s_ashr_i32 s21, s20, 31
	s_lshl_b64 s[20:21], s[20:21], 11
	v_fma_f32 v37, -v35, v36, 1.0
	v_mfma_f32_32x32x16_bf16 v[18:33], v[62:65], v[42:45], v[18:33]
	v_fmac_f32_e32 v36, v37, v36
	v_div_scale_f32 v37, vcc, 1.0, v34, 1.0
	s_add_u32 s27, s23, s20
	s_addc_u32 s36, s29, s21
	s_lshl_b64 s[20:21], s[24:25], 1
	s_add_u32 s20, s27, s20
	v_mfma_f32_32x32x16_bf16 v[2:17], v[66:69], v[38:41], v[2:17]
	s_addc_u32 s21, s36, s21
	s_add_i32 s39, s39, 1
	s_cmp_eq_u32 s39, s22
	v_mfma_f32_32x32x16_bf16 v[18:33], v[70:73], v[38:41], v[18:33]
	v_mul_f32_e32 v38, v37, v36
	v_fma_f32 v39, -v35, v38, v37
	v_fmac_f32_e32 v38, v39, v36
	v_fma_f32 v35, -v35, v38, v37
	v_div_fmas_f32 v35, v35, v36, v38
	v_div_fixup_f32 v34, v35, v34, 1.0
	v_add3_u32 v35, s26, v171, v134
	v_mfma_f32_32x32x16_bf16 v[2:17], v[74:77], v[46:49], v[2:17]
	v_mfma_f32_32x32x16_bf16 v[18:33], v[78:81], v[46:49], v[18:33]
	s_nop 10
	v_mul_f32_e32 v36, v3, v34
	v_mul_f32_e32 v3, v4, v34
	v_mul_f32_e32 v5, v5, v34
	v_cvt_pk_bf16_f32 v3, v3, v5
	v_mul_f32_e32 v2, v2, v34
	v_mul_f32_e32 v6, v6, v34
	v_mul_f32_e32 v9, v9, v34
	v_mul_f32_e32 v18, v18, v34
	v_mul_f32_e32 v19, v19, v34
	v_mul_f32_e32 v4, v20, v34
	v_mul_f32_e32 v5, v21, v34
	v_cvt_pk_bf16_f32 v5, v4, v5
	v_cvt_pk_bf16_f32 v4, v18, v19
	v_mul_f32_e32 v19, v7, v34
	v_mul_f32_e32 v7, v8, v34
	v_cvt_pk_bf16_f32 v2, v2, v36
	v_cvt_pk_bf16_f32 v7, v7, v9
	v_cvt_pk_bf16_f32 v6, v6, v19
	v_add_u32_e32 v9, 0xb000, v35
	v_mul_f32_e32 v18, v22, v34
	v_mul_f32_e32 v20, v23, v34
	v_mul_f32_e32 v8, v24, v34
	ds_write2_b64 v9, v[2:3], v[6:7] offset1:2
	v_mul_f32_e32 v2, v25, v34
	v_cvt_pk_bf16_f32 v3, v8, v2
	v_cvt_pk_bf16_f32 v2, v18, v20
	ds_write2_b64 v9, v[4:5], v[2:3] offset0:8 offset1:10
	v_mul_f32_e32 v2, v10, v34
	v_mul_f32_e32 v5, v11, v34
	v_mul_f32_e32 v4, v26, v34
	v_mul_f32_e32 v6, v27, v34
	v_mul_f32_e32 v7, v28, v34
	v_cvt_pk_bf16_f32 v2, v2, v5
	v_mul_f32_e32 v5, v29, v34
	v_mul_f32_e32 v3, v12, v34
	v_mul_f32_e32 v8, v13, v34
	v_cvt_pk_bf16_f32 v5, v7, v5
	v_cvt_pk_bf16_f32 v4, v4, v6
	v_mul_f32_e32 v6, v14, v34
	v_mul_f32_e32 v10, v15, v34
	v_mul_f32_e32 v7, v16, v34
	v_mul_f32_e32 v13, v17, v34
	v_cvt_pk_bf16_f32 v3, v3, v8
	v_cvt_pk_bf16_f32 v7, v7, v13
	v_cvt_pk_bf16_f32 v6, v6, v10
	v_mul_f32_e32 v8, v30, v34
	v_mul_f32_e32 v11, v31, v34
	v_mul_f32_e32 v12, v32, v34
	ds_write2_b64 v9, v[2:3], v[6:7] offset0:4 offset1:6
	v_mul_f32_e32 v2, v33, v34
	v_cvt_pk_bf16_f32 v3, v12, v2
	v_cvt_pk_bf16_f32 v2, v8, v11
	ds_write2_b64 v9, v[4:5], v[2:3] offset0:12 offset1:14
	s_waitcnt lgkmcnt(0)
	v_add3_u32 v14, s26, v144, v172
	ds_read_b128 v[2:5], v14 offset:45056
	ds_read_b128 v[6:9], v14 offset:46208
	v_lshl_add_u64 v[10:11], s[20:21], 0, v[0:1]
	v_lshl_add_u64 v[12:13], v[10:11], 0, v[152:153]
	s_cselect_b64 s[20:21], -1, 0
	s_waitcnt lgkmcnt(1)
	global_store_dwordx4 v[12:13], v[2:5], off
	v_lshl_add_u64 v[12:13], v[10:11], 0, v[154:155]
	ds_read_b128 v[2:5], v14 offset:47360
	s_waitcnt lgkmcnt(1)
	global_store_dwordx4 v[12:13], v[6:9], off
	ds_read_b128 v[6:9], v14 offset:48512
	v_lshl_add_u64 v[12:13], v[10:11], 0, v[156:157]
	s_waitcnt lgkmcnt(1)
	global_store_dwordx4 v[12:13], v[2:5], off
	s_nop 1
	v_lshl_add_u64 v[2:3], v[10:11], 0, v[158:159]
	s_waitcnt lgkmcnt(0)
	global_store_dwordx4 v[2:3], v[6:9], off
	s_barrier

; #define LAS __attribute__((address_space(3)))
; __device__ __forceinline__ void unit(LAS unsigned char* lds, const bf16* __restrict__ Q, const bf16* __restrict__ Kn, const bf16* __restrict__ Kr, const bf16* __restrict__ Vt, bf16* __restrict__ O,
;                                      int tokbase, int S, int h, int qb, const int tid) {
;     ...
;         const LAS unsigned char* kb = lds + (t & 1) * BUFB;
;         const LAS unsigned char* vb = kb + KBYTES;
;         f32x16 p0 = {}, p1 = {};
;         {
;             bf16x8 kf0[6], kf1[6];
; #pragma unroll
;             for (int d0 = 0; d0 < 6; ++d0) { kf0[d0] = *(const LAS bf16x8*)(kb + r32 * KSTR + d0 * 32 + hi * 16); kf1[d0] = *(const LAS bf16x8*)(kb + (32 + r32) * KSTR + d0 * 32 + hi * 16); }
;             __builtin_amdgcn_sched_barrier(0);
; #pragma unroll
;             for (int d0 = 0; d0 < 6; ++d0) { p0 = __builtin_amdgcn_mfma_f32_32x32x16_bf16(kf0[d0], qf[d0], p0, 0, 0, 0); p1 = __builtin_amdgcn_mfma_f32_32x32x16_bf16(kf1[d0], qf[d0], p1, 0, 0, 0); }
;         }
.LBB0_729:
	s_or_b64 exec, exec, s[26:27]
	global_load_dwordx4 v[126:129], v[162:163], off
	s_and_b32 s37, 1, s36
	s_cselect_b32 s26, 0, 0x5800
	s_add_i32 s45, s26, 0
	v_add3_u32 v185, s45, v168, v169
	ds_read_b128 v[34:37], v185
	ds_read_b128 v[38:41], v185 offset:6656
	ds_read_b128 v[66:69], v185 offset:32
	ds_read_b128 v[70:73], v185 offset:6688
	s_waitcnt lgkmcnt(3)
	v_mfma_f32_32x32x16_bf16 v[50:65], v[34:37], v[118:121], 0
	ds_read_b128 v[74:77], v185 offset:64
	s_waitcnt lgkmcnt(3)
	v_mfma_f32_32x32x16_bf16 v[34:49], v[38:41], v[118:121], 0
	ds_read_b128 v[82:85], v185 offset:6720
	s_waitcnt lgkmcnt(3)
	v_mfma_f32_32x32x16_bf16 v[50:65], v[66:69], v[114:117], v[50:65]
	ds_read_b128 v[78:81], v185 offset:96
	s_waitcnt lgkmcnt(3)
	v_mfma_f32_32x32x16_bf16 v[34:49], v[70:73], v[114:117], v[34:49]
	ds_read_b128 v[86:89], v185 offset:6752
	s_waitcnt lgkmcnt(3)
	v_mfma_f32_32x32x16_bf16 v[50:65], v[74:77], v[110:113], v[50:65]
	ds_read_b128 v[90:93], v185 offset:128
	s_waitcnt lgkmcnt(3)
	v_mfma_f32_32x32x16_bf16 v[34:49], v[82:85], v[110:113], v[34:49]
	ds_read_b128 v[174:177], v185 offset:6784
	s_waitcnt lgkmcnt(3)
	v_mfma_f32_32x32x16_bf16 v[50:65], v[78:81], v[106:109], v[50:65]
	ds_read_b128 v[94:97], v185 offset:160
	s_waitcnt lgkmcnt(3)
	v_mfma_f32_32x32x16_bf16 v[34:49], v[86:89], v[106:109], v[34:49]
	ds_read_b128 v[182:185], v185 offset:6816
	s_waitcnt lgkmcnt(3)
	v_mfma_f32_32x32x16_bf16 v[50:65], v[90:93], v[102:105], v[50:65]
	s_waitcnt lgkmcnt(2)
	v_mfma_f32_32x32x16_bf16 v[34:49], v[174:177], v[102:105], v[34:49]
	s_waitcnt lgkmcnt(1)
	v_mfma_f32_32x32x16_bf16 v[50:65], v[94:97], v[98:101], v[50:65]
	v_max3_f32 v66, v50, v51, v52
	s_nop 0
	v_max3_f32 v66, v66, v53, v54
	s_nop 0
	v_max3_f32 v66, v66, v55, v56
	s_nop 0
	v_max3_f32 v66, v66, v57, v58
	s_waitcnt lgkmcnt(0)
	v_mfma_f32_32x32x16_bf16 v[34:49], v[182:185], v[98:101], v[34:49]
	v_max3_f32 v66, v66, v59, v60
	s_nop 0
	v_max3_f32 v66, v66, v61, v62
	s_nop 0
	v_max3_f32 v66, v66, v63, v64
	s_nop 0
	v_max3_f32 v66, v66, v65, v34
	s_nop 0
	v_max3_f32 v66, v66, v35, v36
	s_nop 0
	v_max3_f32 v66, v66, v37, v38
	s_nop 0
	v_max3_f32 v66, v66, v39, v40
	s_nop 0
	v_max3_f32 v66, v66, v41, v42
	s_nop 0
	v_max3_f32 v66, v66, v43, v44
	s_nop 0
	v_max3_f32 v66, v66, v45, v46
	s_nop 0
	v_max3_f32 v66, v66, v47, v48
	s_nop 0
	v_max3_f32 v66, v66, v49, v49
	v_mov_b32_e32 v67, v66
	s_nop 1
	v_permlane32_swap_b32_e32 v67, v66
	v_max_f32_e32 v66, v66, v67
	s_nop 0
	v_sub_f32_e32 v66, v66, v157
	v_cmp_lt_f32_e32 vcc, s87, v66
	s_cbranch_vccz .LBB0_731
	v_max_f32_e32 v66, v66, v66
	v_max_f32_e32 v67, 0, v66
	v_exp_f32_e64 v66, -v67
	v_add_f32_e32 v157, v157, v67
	v_pk_mul_f32 v[16:17], v[16:17], v[66:67] op_sel_hi:[1,0]
	v_pk_mul_f32 v[14:15], v[14:15], v[66:67] op_sel_hi:[1,0]
	v_pk_mul_f32 v[12:13], v[12:13], v[66:67] op_sel_hi:[1,0]
	v_pk_mul_f32 v[10:11], v[10:11], v[66:67] op_sel_hi:[1,0]
	v_pk_mul_f32 v[8:9], v[8:9], v[66:67] op_sel_hi:[1,0]
	v_pk_mul_f32 v[6:7], v[6:7], v[66:67] op_sel_hi:[1,0]
	v_pk_mul_f32 v[4:5], v[4:5], v[66:67] op_sel_hi:[1,0]
	v_pk_mul_f32 v[2:3], v[2:3], v[66:67] op_sel_hi:[1,0]
	v_pk_mul_f32 v[32:33], v[32:33], v[66:67] op_sel_hi:[1,0]
	v_pk_mul_f32 v[30:31], v[30:31], v[66:67] op_sel_hi:[1,0]
	v_pk_mul_f32 v[28:29], v[28:29], v[66:67] op_sel_hi:[1,0]
	v_pk_mul_f32 v[26:27], v[26:27], v[66:67] op_sel_hi:[1,0]
	v_pk_mul_f32 v[24:25], v[24:25], v[66:67] op_sel_hi:[1,0]
	v_pk_mul_f32 v[22:23], v[22:23], v[66:67] op_sel_hi:[1,0]
	v_pk_mul_f32 v[20:21], v[20:21], v[66:67] op_sel_hi:[1,0]
	v_pk_mul_f32 v[18:19], v[18:19], v[66:67] op_sel_hi:[1,0]
	v_mul_f32_e32 v153, v153, v66

; #define LAS __attribute__((address_space(3)))
; __device__ __forceinline__ void unit(LAS unsigned char* lds, const bf16* __restrict__ Q, const bf16* __restrict__ Kn, const bf16* __restrict__ Kr, const bf16* __restrict__ Vt, bf16* __restrict__ O,
;                                      int tokbase, int S, int h, int qb, const int tid) {
;     ...
;         {
;             bf16x8 vfa[2][2], vfb[2][2];
; #pragma unroll
;             for (int kt = 0; kt < 2; ++kt)
; #pragma unroll
;                 for (int s = 0; s < 2; ++s) {
;                     const int kcol = (kt * 32 + 16 * s + 4 * hi) * 2;
;                     const u32x2 a0 = *(const LAS u32x2*)(vb + r32 * VSTR + kcol), a1 = *(const LAS u32x2*)(vb + r32 * VSTR + kcol + 16);
;                     const u32x2 b0 = *(const LAS u32x2*)(vb + (32 + r32) * VSTR + kcol), b1 = *(const LAS u32x2*)(vb + (32 + r32) * VSTR + kcol + 16);
;                     vfa[kt][s] = __builtin_bit_cast(bf16x8, (u32x4){a0.x, a0.y, a1.x, a1.y});
;                     vfb[kt][s] = __builtin_bit_cast(bf16x8, (u32x4){b0.x, b0.y, b1.x, b1.y});
;                 }
;             __builtin_amdgcn_sched_barrier(0);
; #pragma unroll
;             for (int kt = 0; kt < 2; ++kt)
; #pragma unroll
;                 for (int s = 0; s < 2; ++s) {
;                     o0 = __builtin_amdgcn_mfma_f32_32x32x16_bf16(vfa[kt][s], pb[kt][s], o0, 0, 0, 0);
;                     o1 = __builtin_amdgcn_mfma_f32_32x32x16_bf16(vfb[kt][s], pb[kt][s], o1, 0, 0, 0);
;                 }
;         }
;         if (t + 1 < NT) ATT_WRITE((t + 1) & 1);
.LBB0_734:
	v_cvt_pk_bf16_f32 v46, v74, v75
	v_cvt_pk_bf16_f32 v48, v78, v79
	v_cvt_pk_bf16_f32 v38, v66, v67
	v_cvt_pk_bf16_f32 v39, v68, v69
	v_cvt_pk_bf16_f32 v40, v70, v71
	v_cvt_pk_bf16_f32 v41, v72, v73
	v_cvt_pk_bf16_f32 v47, v76, v77
	v_cvt_pk_bf16_f32 v49, v80, v81
	v_add3_u32 v81, s45, v170, v169
	ds_read_b128 v[50:53], v81 offset:13312
	ds_read_b128 v[58:61], v81 offset:17920
	ds_read_b128 v[54:57], v81 offset:13344
	ds_read_b128 v[62:65], v81 offset:17952
	v_cvt_pk_bf16_f32 v34, v82, v83
	v_cvt_pk_bf16_f32 v35, v84, v85
	v_cvt_pk_bf16_f32 v36, v86, v87
	v_cvt_pk_bf16_f32 v37, v88, v89
	v_cvt_pk_bf16_f32 v42, v90, v91
	v_cvt_pk_bf16_f32 v43, v92, v93
	v_cvt_pk_bf16_f32 v44, v94, v95
	v_cvt_pk_bf16_f32 v45, v96, v97
	s_waitcnt lgkmcnt(3)
	v_mfma_f32_32x32x16_bf16 v[2:17], v[50:53], v[34:37], v[2:17]
	ds_read_b128 v[66:69], v81 offset:13376
	s_cmp_eq_u32 s37, 1
	s_cselect_b32 s26, 0x5800, 0
	s_add_i32 s37, s26, 0
	s_waitcnt lgkmcnt(3)
	v_mfma_f32_32x32x16_bf16 v[18:33], v[58:61], v[34:37], v[18:33]
	ds_read_b128 v[70:73], v81 offset:17984
	v_add3_u32 v34, s37, v139, v144
	s_waitcnt lgkmcnt(3)
	v_mfma_f32_32x32x16_bf16 v[2:17], v[54:57], v[42:45], v[2:17]
	ds_read_b128 v[74:77], v81 offset:13408
	s_waitcnt lgkmcnt(3)
	v_mfma_f32_32x32x16_bf16 v[18:33], v[62:65], v[42:45], v[18:33]
	ds_read_b128 v[78:81], v81 offset:18016
	s_waitcnt vmcnt(1)
	ds_write_b128 v34, v[130:133]
	s_waitcnt lgkmcnt(4)
	v_mfma_f32_32x32x16_bf16 v[2:17], v[66:69], v[38:41], v[2:17]
	s_waitcnt lgkmcnt(3)
	v_mfma_f32_32x32x16_bf16 v[18:33], v[70:73], v[38:41], v[18:33]
	s_waitcnt lgkmcnt(2)
	v_mfma_f32_32x32x16_bf16 v[2:17], v[74:77], v[46:49], v[2:17]
	s_waitcnt lgkmcnt(1)
	v_mfma_f32_32x32x16_bf16 v[18:33], v[78:81], v[46:49], v[18:33]
	s_and_saveexec_b64 s[26:27], s[6:7]
	s_cbranch_execz .LBB0_726
	v_add3_u32 v34, s37, v166, v138
	ds_write_b128 v34, v[122:125] offset:128
	s_branch .LBB0_726
